# GEMM K-loop: per-phase s_setprio toggles removed (A/B test on top of previous version)
# speedup vs baseline: 1.0105x; 1.0028x over previous
.LBB0_357:
	s_add_i32 s55, s26, 2
	s_add_u32 s59, s28, 0x80
	s_addc_u32 s27, s29, 0
	s_add_i32 s80, 0, 0x10000
	s_cmp_eq_u32 s62, s26
	s_cselect_b32 s27, s1, s27
	s_cselect_b32 s26, s0, s59
	v_add_u32_e32 v96, s80, v162
	s_cselect_b32 s79, s77, s54
	s_cselect_b32 s78, s76, s41
	s_add_i32 s59, 0, 0x14000
	s_waitcnt lgkmcnt(0)
	ds_read_b128 v[0:3], v96
	ds_read_b128 v[4:7], v96 offset:1024
	ds_read_b128 v[98:101], v96 offset:2048
	ds_read_b128 v[158:161], v96 offset:3072
	v_add_u32_e32 v96, s59, v162
	ds_read_b128 v[164:167], v96
	ds_read_b128 v[168:171], v96 offset:1024
	ds_read_b128 v[172:175], v96 offset:2048
	ds_read_b128 v[198:201], v96 offset:3072
	v_lshl_add_u64 v[102:103], s[28:29], 0, v[154:155]
	s_add_i32 m0, s75, 0xc000
	ds_read_b128 v[202:205], v163
	ds_read_b128 v[206:209], v163 offset:1024
	ds_read_b128 v[210:213], v163 offset:2048
	ds_read_b128 v[214:217], v163 offset:3072
	ds_read_b128 v[218:221], v163 offset:4096
	ds_read_b128 v[222:225], v163 offset:5120
	ds_read_b128 v[226:229], v163 offset:6144
	ds_read_b128 v[230:233], v163 offset:7168
	global_load_lds_dwordx4 v[102:103], off
	v_lshl_add_u64 v[102:103], s[28:29], 0, v[156:157]
	s_add_i32 m0, s75, 0xe000
	s_nop 0
	global_load_lds_dwordx4 v[102:103], off
	s_waitcnt vmcnt(8)
	s_waitcnt lgkmcnt(0)
	s_barrier
	s_waitcnt lgkmcnt(0)
	v_mfma_f32_16x16x32_bf16 v[140:143], v[0:3], v[202:205], v[140:143]
	v_mfma_f32_16x16x32_bf16 v[136:139], v[98:101], v[202:205], v[136:139]
	v_mfma_f32_16x16x32_bf16 v[132:135], v[0:3], v[210:213], v[132:135]
	v_mfma_f32_16x16x32_bf16 v[128:131], v[98:101], v[210:213], v[128:131]
	v_mfma_f32_16x16x32_bf16 v[124:127], v[0:3], v[218:221], v[124:127]
	v_mfma_f32_16x16x32_bf16 v[120:123], v[98:101], v[218:221], v[120:123]
	v_mfma_f32_16x16x32_bf16 v[116:119], v[0:3], v[226:229], v[116:119]
	v_mfma_f32_16x16x32_bf16 v[112:115], v[98:101], v[226:229], v[112:115]
	v_mfma_f32_16x16x32_bf16 v[140:143], v[4:7], v[206:209], v[140:143]
	v_mfma_f32_16x16x32_bf16 v[136:139], v[158:161], v[206:209], v[136:139]
	v_mfma_f32_16x16x32_bf16 v[132:135], v[4:7], v[214:217], v[132:135]
	v_mfma_f32_16x16x32_bf16 v[128:131], v[158:161], v[214:217], v[128:131]
	v_mfma_f32_16x16x32_bf16 v[124:127], v[4:7], v[222:225], v[124:127]
	v_mfma_f32_16x16x32_bf16 v[120:123], v[158:161], v[222:225], v[120:123]
	v_mfma_f32_16x16x32_bf16 v[116:119], v[4:7], v[230:233], v[116:119]
	v_mfma_f32_16x16x32_bf16 v[112:115], v[158:161], v[230:233], v[112:115]
	v_mfma_f32_16x16x32_bf16 v[68:71], v[164:167], v[202:205], v[68:71]
	v_mfma_f32_16x16x32_bf16 v[64:67], v[172:175], v[202:205], v[64:67]
	v_mfma_f32_16x16x32_bf16 v[60:63], v[164:167], v[210:213], v[60:63]
	v_mfma_f32_16x16x32_bf16 v[56:59], v[172:175], v[210:213], v[56:59]
	v_mfma_f32_16x16x32_bf16 v[52:55], v[164:167], v[218:221], v[52:55]
	v_mfma_f32_16x16x32_bf16 v[48:51], v[172:175], v[218:221], v[48:51]
	v_mfma_f32_16x16x32_bf16 v[44:47], v[164:167], v[226:229], v[44:47]
	v_mfma_f32_16x16x32_bf16 v[40:43], v[172:175], v[226:229], v[40:43]
	v_mfma_f32_16x16x32_bf16 v[68:71], v[168:171], v[206:209], v[68:71]
	v_mfma_f32_16x16x32_bf16 v[64:67], v[198:201], v[206:209], v[64:67]
	v_mfma_f32_16x16x32_bf16 v[60:63], v[168:171], v[214:217], v[60:63]
	v_mfma_f32_16x16x32_bf16 v[56:59], v[198:201], v[214:217], v[56:59]
	v_mfma_f32_16x16x32_bf16 v[52:55], v[168:171], v[222:225], v[52:55]
	v_mfma_f32_16x16x32_bf16 v[48:51], v[198:201], v[222:225], v[48:51]
	v_mfma_f32_16x16x32_bf16 v[44:47], v[168:171], v[230:233], v[44:47]
	v_mfma_f32_16x16x32_bf16 v[40:43], v[198:201], v[230:233], v[40:43]
	s_barrier
	s_add_i32 s80, s80, s74
	v_lshl_add_u64 v[176:177], s[78:79], 0, v[146:147]
	s_mov_b32 m0, s80
	ds_read_b128 v[202:205], v163 offset:16384
	ds_read_b128 v[206:209], v163 offset:17408
	ds_read_b128 v[210:213], v163 offset:18432
	ds_read_b128 v[214:217], v163 offset:19456
	ds_read_b128 v[218:221], v163 offset:20480
	ds_read_b128 v[222:225], v163 offset:21504
	ds_read_b128 v[226:229], v163 offset:22528
	ds_read_b128 v[230:233], v163 offset:23552
	global_load_lds_dwordx4 v[176:177], off
	s_add_i32 m0, s80, 0x2000
	v_lshl_add_u64 v[186:187], s[78:79], 0, v[150:151]
	s_add_u32 s78, s78, s4
	s_addc_u32 s79, s79, 0
	s_add_i32 s59, s59, s74
	global_load_lds_dwordx4 v[186:187], off
	v_lshl_add_u64 v[234:235], s[78:79], 0, v[146:147]
	s_mov_b32 m0, s59
	v_lshl_add_u64 v[236:237], s[78:79], 0, v[150:151]
	global_load_lds_dwordx4 v[234:235], off
	s_add_i32 m0, s59, 0x2000
	v_lshl_add_u64 v[238:239], s[26:27], 0, v[144:145]
	global_load_lds_dwordx4 v[236:237], off
	s_mov_b32 m0, s75
	v_lshl_add_u64 v[240:241], s[26:27], 0, v[148:149]
	global_load_lds_dwordx4 v[238:239], off
	s_mov_b32 m0, s3
	s_nop 0
	global_load_lds_dwordx4 v[240:241], off
	s_waitcnt vmcnt(8)
	s_waitcnt lgkmcnt(0)
	s_barrier
	s_waitcnt lgkmcnt(0)
	v_mfma_f32_16x16x32_bf16 v[108:111], v[0:3], v[202:205], v[108:111]
	v_mfma_f32_16x16x32_bf16 v[102:105], v[98:101], v[202:205], v[104:107]
	v_mfma_f32_16x16x32_bf16 v[92:95], v[0:3], v[210:213], v[92:95]
	v_mfma_f32_16x16x32_bf16 v[88:91], v[98:101], v[210:213], v[88:91]
	v_mfma_f32_16x16x32_bf16 v[84:87], v[0:3], v[218:221], v[84:87]
	v_mfma_f32_16x16x32_bf16 v[80:83], v[98:101], v[218:221], v[80:83]
	v_mfma_f32_16x16x32_bf16 v[0:3], v[0:3], v[226:229], v[76:79]
	v_mfma_f32_16x16x32_bf16 v[108:111], v[4:7], v[206:209], v[108:111]
	v_mfma_f32_16x16x32_bf16 v[102:105], v[158:161], v[206:209], v[102:105]
	v_mfma_f32_16x16x32_bf16 v[92:95], v[4:7], v[214:217], v[92:95]
	v_mfma_f32_16x16x32_bf16 v[88:91], v[158:161], v[214:217], v[88:91]
	v_mfma_f32_16x16x32_bf16 v[84:87], v[4:7], v[222:225], v[84:87]
	v_mfma_f32_16x16x32_bf16 v[80:83], v[158:161], v[222:225], v[80:83]
	v_mfma_f32_16x16x32_bf16 v[0:3], v[4:7], v[230:233], v[0:3]
	v_mfma_f32_16x16x32_bf16 v[4:7], v[98:101], v[226:229], v[72:75]
	v_mfma_f32_16x16x32_bf16 v[4:7], v[158:161], v[230:233], v[4:7]
	v_mfma_f32_16x16x32_bf16 v[36:39], v[164:167], v[202:205], v[36:39]
	v_mfma_f32_16x16x32_bf16 v[32:35], v[172:175], v[202:205], v[32:35]
	v_mfma_f32_16x16x32_bf16 v[28:31], v[164:167], v[210:213], v[28:31]
	v_mfma_f32_16x16x32_bf16 v[24:27], v[172:175], v[210:213], v[24:27]
	v_mfma_f32_16x16x32_bf16 v[20:23], v[164:167], v[218:221], v[20:23]
	v_mfma_f32_16x16x32_bf16 v[16:19], v[172:175], v[218:221], v[16:19]
	v_mfma_f32_16x16x32_bf16 v[12:15], v[164:167], v[226:229], v[12:15]
	v_mfma_f32_16x16x32_bf16 v[8:11], v[172:175], v[226:229], v[8:11]
	v_mfma_f32_16x16x32_bf16 v[36:39], v[168:171], v[206:209], v[36:39]
	v_mfma_f32_16x16x32_bf16 v[32:35], v[198:201], v[206:209], v[32:35]
	v_mfma_f32_16x16x32_bf16 v[28:31], v[168:171], v[214:217], v[28:31]
	v_mfma_f32_16x16x32_bf16 v[24:27], v[198:201], v[214:217], v[24:27]
	v_mfma_f32_16x16x32_bf16 v[20:23], v[168:171], v[222:225], v[20:23]
	v_mfma_f32_16x16x32_bf16 v[16:19], v[198:201], v[222:225], v[16:19]
	v_mfma_f32_16x16x32_bf16 v[12:15], v[168:171], v[230:233], v[12:15]
	v_mfma_f32_16x16x32_bf16 v[8:11], v[198:201], v[230:233], v[8:11]
	s_barrier
	s_add_i32 s59, 0, 0x18000
	v_add_u32_e32 v96, s59, v162
	s_add_i32 s78, 0, 0x1c000
	ds_read_b128 v[72:75], v96
	ds_read_b128 v[76:79], v96 offset:1024
	ds_read_b128 v[98:101], v96 offset:2048
	ds_read_b128 v[158:161], v96 offset:3072
	v_add_u32_e32 v96, s78, v162
	ds_read_b128 v[164:167], v96
	ds_read_b128 v[168:171], v96 offset:1024
	ds_read_b128 v[172:175], v96 offset:2048
	ds_read_b128 v[198:201], v96 offset:3072
	s_add_u32 s26, s26, s4
	s_addc_u32 s27, s27, 0
	s_mov_b32 m0, s23
	v_lshl_add_u64 v[106:107], s[26:27], 0, v[144:145]
	ds_read_b128 v[202:205], v163 offset:32768
	ds_read_b128 v[206:209], v163 offset:33792
	ds_read_b128 v[210:213], v163 offset:34816
	ds_read_b128 v[214:217], v163 offset:35840
	ds_read_b128 v[218:221], v163 offset:36864
	ds_read_b128 v[222:225], v163 offset:37888
	ds_read_b128 v[226:229], v163 offset:38912
	ds_read_b128 v[230:233], v163 offset:39936
	global_load_lds_dwordx4 v[106:107], off
	v_lshl_add_u64 v[106:107], s[26:27], 0, v[148:149]
	s_mov_b32 m0, s72
	s_nop 0
	global_load_lds_dwordx4 v[106:107], off
	s_waitcnt vmcnt(8)
	s_waitcnt lgkmcnt(0)
	s_barrier
	s_waitcnt lgkmcnt(0)
	v_mfma_f32_16x16x32_bf16 v[140:143], v[72:75], v[202:205], v[140:143]
	v_mfma_f32_16x16x32_bf16 v[136:139], v[98:101], v[202:205], v[136:139]
	v_mfma_f32_16x16x32_bf16 v[132:135], v[72:75], v[210:213], v[132:135]
	v_mfma_f32_16x16x32_bf16 v[128:131], v[98:101], v[210:213], v[128:131]
	v_mfma_f32_16x16x32_bf16 v[124:127], v[72:75], v[218:221], v[124:127]
	v_mfma_f32_16x16x32_bf16 v[120:123], v[98:101], v[218:221], v[120:123]
	v_mfma_f32_16x16x32_bf16 v[116:119], v[72:75], v[226:229], v[116:119]
	v_mfma_f32_16x16x32_bf16 v[112:115], v[98:101], v[226:229], v[112:115]
	v_mfma_f32_16x16x32_bf16 v[140:143], v[76:79], v[206:209], v[140:143]
	v_mfma_f32_16x16x32_bf16 v[136:139], v[158:161], v[206:209], v[136:139]
	v_mfma_f32_16x16x32_bf16 v[132:135], v[76:79], v[214:217], v[132:135]
	v_mfma_f32_16x16x32_bf16 v[128:131], v[158:161], v[214:217], v[128:131]
	v_mfma_f32_16x16x32_bf16 v[124:127], v[76:79], v[222:225], v[124:127]
	v_mfma_f32_16x16x32_bf16 v[120:123], v[158:161], v[222:225], v[120:123]
	v_mfma_f32_16x16x32_bf16 v[116:119], v[76:79], v[230:233], v[116:119]
	v_mfma_f32_16x16x32_bf16 v[112:115], v[158:161], v[230:233], v[112:115]
	v_mfma_f32_16x16x32_bf16 v[68:71], v[164:167], v[202:205], v[68:71]
	v_mfma_f32_16x16x32_bf16 v[64:67], v[172:175], v[202:205], v[64:67]
	v_mfma_f32_16x16x32_bf16 v[60:63], v[164:167], v[210:213], v[60:63]
	v_mfma_f32_16x16x32_bf16 v[56:59], v[172:175], v[210:213], v[56:59]
	v_mfma_f32_16x16x32_bf16 v[52:55], v[164:167], v[218:221], v[52:55]
	v_mfma_f32_16x16x32_bf16 v[48:51], v[172:175], v[218:221], v[48:51]
	v_mfma_f32_16x16x32_bf16 v[44:47], v[164:167], v[226:229], v[44:47]
	v_mfma_f32_16x16x32_bf16 v[40:43], v[172:175], v[226:229], v[40:43]
	v_mfma_f32_16x16x32_bf16 v[68:71], v[168:171], v[206:209], v[68:71]
	v_mfma_f32_16x16x32_bf16 v[64:67], v[198:201], v[206:209], v[64:67]
	v_mfma_f32_16x16x32_bf16 v[60:63], v[168:171], v[214:217], v[60:63]
	v_mfma_f32_16x16x32_bf16 v[56:59], v[198:201], v[214:217], v[56:59]
	v_mfma_f32_16x16x32_bf16 v[52:55], v[168:171], v[222:225], v[52:55]
	v_mfma_f32_16x16x32_bf16 v[48:51], v[198:201], v[222:225], v[48:51]
	v_mfma_f32_16x16x32_bf16 v[44:47], v[168:171], v[230:233], v[44:47]
	v_mfma_f32_16x16x32_bf16 v[40:43], v[198:201], v[230:233], v[40:43]
	s_barrier
	s_add_i32 s26, s59, s74
	v_lshl_add_u64 v[106:107], v[176:177], 0, s[20:21]
	s_mov_b32 m0, s26
	ds_read_b128 v[202:205], v163 offset:49152
	ds_read_b128 v[206:209], v163 offset:50176
	ds_read_b128 v[210:213], v163 offset:51200
	ds_read_b128 v[214:217], v163 offset:52224
	ds_read_b128 v[218:221], v163 offset:53248
	ds_read_b128 v[222:225], v163 offset:54272
	ds_read_b128 v[226:229], v163 offset:55296
	ds_read_b128 v[230:233], v163 offset:56320
	global_load_lds_dwordx4 v[106:107], off
	v_lshl_add_u64 v[106:107], v[186:187], 0, s[20:21]
	s_add_i32 m0, s26, 0x2000
	s_add_i32 s26, s78, s74
	global_load_lds_dwordx4 v[106:107], off
	v_lshl_add_u64 v[106:107], v[234:235], 0, s[20:21]
	s_mov_b32 m0, s26
	s_nop 0
	global_load_lds_dwordx4 v[106:107], off
	v_lshl_add_u64 v[106:107], v[236:237], 0, s[20:21]
	s_add_i32 m0, s26, 0x2000
	s_nop 0
	global_load_lds_dwordx4 v[106:107], off
	v_lshl_add_u64 v[106:107], v[238:239], 0, s[20:21]
	s_mov_b32 m0, s60
	s_nop 0
	global_load_lds_dwordx4 v[106:107], off
	v_lshl_add_u64 v[106:107], v[240:241], 0, s[20:21]
	s_mov_b32 m0, s61
	s_nop 0
	global_load_lds_dwordx4 v[106:107], off
	s_waitcnt vmcnt(8)
	s_waitcnt lgkmcnt(0)
	s_barrier
	s_waitcnt lgkmcnt(0)
	v_mfma_f32_16x16x32_bf16 v[106:109], v[72:75], v[202:205], v[108:111]
	v_mfma_f32_16x16x32_bf16 v[92:95], v[72:75], v[210:213], v[92:95]
	v_mfma_f32_16x16x32_bf16 v[84:87], v[72:75], v[218:221], v[84:87]
	v_mfma_f32_16x16x32_bf16 v[0:3], v[72:75], v[226:229], v[0:3]
	v_mfma_f32_16x16x32_bf16 v[108:111], v[76:79], v[206:209], v[106:109]
	v_mfma_f32_16x16x32_bf16 v[102:105], v[98:101], v[202:205], v[102:105]
	v_mfma_f32_16x16x32_bf16 v[92:95], v[76:79], v[214:217], v[92:95]
	v_mfma_f32_16x16x32_bf16 v[88:91], v[98:101], v[210:213], v[88:91]
	v_mfma_f32_16x16x32_bf16 v[84:87], v[76:79], v[222:225], v[84:87]
	v_mfma_f32_16x16x32_bf16 v[80:83], v[98:101], v[218:221], v[80:83]
	v_mfma_f32_16x16x32_bf16 v[76:79], v[76:79], v[230:233], v[0:3]
	v_mfma_f32_16x16x32_bf16 v[0:3], v[98:101], v[226:229], v[4:7]
	v_mfma_f32_16x16x32_bf16 v[104:107], v[158:161], v[206:209], v[102:105]
	v_mfma_f32_16x16x32_bf16 v[88:91], v[158:161], v[214:217], v[88:91]
	v_mfma_f32_16x16x32_bf16 v[80:83], v[158:161], v[222:225], v[80:83]
	v_mfma_f32_16x16x32_bf16 v[72:75], v[158:161], v[230:233], v[0:3]
	v_mfma_f32_16x16x32_bf16 v[0:3], v[164:167], v[202:205], v[36:39]
	v_mfma_f32_16x16x32_bf16 v[36:39], v[168:171], v[206:209], v[0:3]
	v_mfma_f32_16x16x32_bf16 v[0:3], v[172:175], v[202:205], v[32:35]
	v_mfma_f32_16x16x32_bf16 v[32:35], v[198:201], v[206:209], v[0:3]
	v_mfma_f32_16x16x32_bf16 v[0:3], v[164:167], v[210:213], v[28:31]
	v_mfma_f32_16x16x32_bf16 v[28:31], v[168:171], v[214:217], v[0:3]
	v_mfma_f32_16x16x32_bf16 v[0:3], v[172:175], v[210:213], v[24:27]
	v_mfma_f32_16x16x32_bf16 v[24:27], v[198:201], v[214:217], v[0:3]
	v_mfma_f32_16x16x32_bf16 v[0:3], v[164:167], v[218:221], v[20:23]
	v_mfma_f32_16x16x32_bf16 v[20:23], v[168:171], v[222:225], v[0:3]
	v_mfma_f32_16x16x32_bf16 v[0:3], v[172:175], v[218:221], v[16:19]
	v_mfma_f32_16x16x32_bf16 v[16:19], v[198:201], v[222:225], v[0:3]
	v_mfma_f32_16x16x32_bf16 v[0:3], v[164:167], v[226:229], v[12:15]
	v_mfma_f32_16x16x32_bf16 v[12:15], v[168:171], v[230:233], v[0:3]
	v_mfma_f32_16x16x32_bf16 v[0:3], v[172:175], v[226:229], v[8:11]
	v_mfma_f32_16x16x32_bf16 v[8:11], v[198:201], v[230:233], v[0:3]
	s_barrier
	s_add_u32 s28, s28, 0x100
	s_addc_u32 s29, s29, 0
	s_add_u32 s41, s41, 0x100
	s_addc_u32 s54, s54, 0
	s_cmp_ge_u32 s55, s73
	s_mov_b32 s26, s55
	s_cbranch_scc0 .LBB0_357
	s_and_b64 vcc, exec, s[18:19]
	s_cbranch_vccz .LBB0_360
	s_barrier
